# down/w_out GEMM tile groups 4 row-blocks x 8 column tiles per XCD round (ACT streamed once instead of twice); scheduler constants only
# speedup vs baseline: 1.0023x; 1.0023x over previous
; __device__ __forceinline__ unsigned xb_ld(unsigned* p)              { return __hip_atomic_load(p, __ATOMIC_RELAXED, __HIP_MEMORY_SCOPE_AGENT); }
; __device__ __forceinline__ void xcd_barrier_complete(unsigned* bar, unsigned x, unsigned& nloc, unsigned& nx) {
;     ...
;         sum = 0u; cnt = 0u; mine = 0u;
; #pragma unroll
;         for (unsigned j = 0; j < 16; ++j) { const unsigned c = xb_ld(&bar[XB_XCNT(j)]); sum += c; cnt += (c > 0u) ? 1u : 0u; mine = (j == x) ? c : mine; }
;         if (sum == G) break;
;         __builtin_amdgcn_s_sleep(1);
;         if ((++sp & 255u) == 0u) { if (xb_ld(&bar[XB_TMO])) break; if (sp > XB_SPIN_CAP) { atomicAdd(&bar[XB_TMO], 1u); break; } }
;     }
;     nloc = mine > 0u ? mine : 1u; nx = cnt > 0u ? cnt : 1u;
; __global__ void __launch_bounds__(512, 2) fwd(Args a) {
;     ...
;     float* mod = (float*)(ws + WS_MOD);
;     bf16* H = (bf16*)(ws + WS_H); bf16* ACT = (bf16*)(ws + WS_ACT);
;     bf16* UA = (bf16*)(ws + WS_UA); bf16* UB = (bf16*)(ws + WS_UB); bf16* UC = (bf16*)(ws + WS_UC); bf16* UG = (bf16*)(ws + WS_UG); bf16* Y = (bf16*)(ws + WS_Y); _Float16* XH = (_Float16*)(ws + WS_XH);
;     const ScanBufs sb{(float*)(ws + WS_DB), (float*)(ws + WS_DC)};
;     int ph = 0;
;     ...
;     int tid_ = tid, lane_ = lane, wave_ = wave;
.LBB0_95:
	s_add_u32 s58, s42, 0x1b800000
	s_addc_u32 s59, s43, 0
	s_add_u32 s26, s42, 0x23800000
	s_addc_u32 s27, s43, 0
	s_add_u32 s70, s42, 0x29800000
	s_addc_u32 s71, s43, 0
	s_add_u32 s72, s42, 0x31800000
	s_addc_u32 s73, s43, 0
	s_add_u32 s92, s42, 0x38800000
	s_addc_u32 s93, s43, 0
	s_add_u32 s2, s42, 0x44800000
	s_addc_u32 s25, s43, 0
	s_add_u32 s0, s42, 0x4ae00000
	s_addc_u32 s1, s43, 0
	v_writelane_b32 v252, s0, 63
	v_mov_b32_e32 v214, v0
	v_readlane_b32 s8, v252, 19
	v_writelane_b32 v253, s1, 0
	s_add_u32 s0, s42, 0x4a800000
	v_writelane_b32 v253, s0, 1
	s_addc_u32 s0, s43, 0
	v_writelane_b32 v253, s0, 2
	s_add_u32 s0, s42, 0x4ac00000
	v_writelane_b32 v253, s0, 3
	s_addc_u32 s0, s43, 0
	v_writelane_b32 v253, s0, 4
	v_readlane_b32 s9, v252, 20
	v_readfirstlane_b32 s0, v214
	v_readlane_b32 s16, v252, 27
	v_readlane_b32 s17, v252, 28
	s_ashr_i32 s6, s0, 6
	s_mov_b64 s[8:9], s[16:17]
	s_add_u32 s0, s8, 0x6000
	s_addc_u32 s1, s9, 0
	v_writelane_b32 v253, s0, 5
	v_readlane_b32 s10, v252, 21
	v_readlane_b32 s11, v252, 22
	v_writelane_b32 v253, s1, 6
	s_ashr_i32 s0, s67, 5
	s_lshl_b32 s1, s67, 7
	s_add_u32 s4, s64, 0x200
	v_writelane_b32 v253, s1, 7
	s_addc_u32 s5, s65, 0
	v_writelane_b32 v253, s4, 8
	v_readlane_b32 s12, v252, 23
	v_readlane_b32 s13, v252, 24
	v_writelane_b32 v253, s5, 9
	s_add_u32 s4, s64, 0x1000
	s_addc_u32 s5, s65, 0
	v_writelane_b32 v253, s4, 10
	v_readlane_b32 s14, v252, 25
	v_readlane_b32 s15, v252, 26
	v_writelane_b32 v253, s5, 11
	s_add_u32 s4, s64, 0x1100
	s_addc_u32 s5, s65, 0
	v_writelane_b32 v253, s4, 12
	v_readlane_b32 s18, v252, 29
	v_readlane_b32 s19, v252, 30
	v_writelane_b32 v253, s5, 13
	s_add_u32 s4, s64, 0x1200
	s_addc_u32 s5, s65, 0
	v_writelane_b32 v253, s4, 14
	v_mbcnt_lo_u32_b32 v1, -1, 0
	v_mbcnt_hi_u32_b32 v215, -1, v1
	v_writelane_b32 v253, s5, 15
	s_add_u32 s4, s64, 0x1300
	s_addc_u32 s5, s65, 0
	v_writelane_b32 v253, s4, 16
	s_cmp_eq_u32 s24, 15
	v_and_b32_e32 v1, 64, v215
	v_writelane_b32 v253, s5, 17
	s_cselect_b64 s[4:5], -1, 0
	v_writelane_b32 v253, s4, 18
	s_cmp_eq_u32 s24, 14
	v_and_b32_e32 v68, 63, v214
	v_writelane_b32 v253, s5, 19
	s_cselect_b64 s[4:5], -1, 0
	v_writelane_b32 v253, s4, 20
	s_cmp_eq_u32 s24, 13
	v_mov_b32_e32 v169, 0
	v_writelane_b32 v253, s5, 21
	s_cselect_b64 s[4:5], -1, 0
	v_writelane_b32 v253, s4, 22
	s_cmp_eq_u32 s24, 12
	v_mov_b32_e32 v223, 0x358637bd
	v_writelane_b32 v253, s5, 23
	s_cselect_b64 s[4:5], -1, 0
	v_writelane_b32 v253, s4, 24
	s_cmp_eq_u32 s24, 11
	v_mov_b32_e32 v224, 0x260
	v_writelane_b32 v253, s5, 25
	s_cselect_b64 s[4:5], -1, 0
	v_writelane_b32 v253, s4, 26
	s_cmp_eq_u32 s24, 10
	v_mov_b32_e32 v225, 1
	v_writelane_b32 v253, s5, 27
	s_cselect_b64 s[4:5], -1, 0
	v_writelane_b32 v253, s4, 28
	s_cmp_eq_u32 s24, 9
	v_add_u32_e32 v216, 64, v1
	v_writelane_b32 v253, s5, 29
	s_cselect_b64 s[4:5], -1, 0
	v_writelane_b32 v253, s4, 30
	s_cmp_eq_u32 s24, 8
	v_xor_b32_e32 v222, 1, v215
	v_writelane_b32 v253, s5, 31
	s_cselect_b64 s[4:5], -1, 0
	v_writelane_b32 v253, s4, 32
	s_cmp_eq_u32 s24, 7
	v_xor_b32_e32 v221, 2, v215
	v_writelane_b32 v253, s5, 33
	s_cselect_b64 s[4:5], -1, 0
	v_writelane_b32 v253, s4, 34
	s_cmp_eq_u32 s24, 6
	v_xor_b32_e32 v220, 4, v215
	v_writelane_b32 v253, s5, 35
	s_cselect_b64 s[4:5], -1, 0
	v_writelane_b32 v253, s4, 36
	s_cmp_eq_u32 s24, 5
	v_xor_b32_e32 v219, 8, v215
	v_writelane_b32 v253, s5, 37
	s_cselect_b64 s[4:5], -1, 0
	v_writelane_b32 v253, s4, 38
	s_cmp_eq_u32 s24, 4
	v_xor_b32_e32 v218, 16, v215
	v_writelane_b32 v253, s5, 39
	s_cselect_b64 s[4:5], -1, 0
	v_writelane_b32 v253, s4, 40
	s_cmp_eq_u32 s24, 3
	v_xor_b32_e32 v217, 32, v215
	v_writelane_b32 v253, s5, 41
	s_cselect_b64 s[4:5], -1, 0
	v_writelane_b32 v253, s4, 42
	s_cmp_eq_u32 s24, 2
	v_mov_b64_e32 v[174:175], 0x400
	v_writelane_b32 v253, s5, 43
	s_cselect_b64 s[4:5], -1, 0
	v_writelane_b32 v253, s4, 44
	s_cmp_eq_u32 s24, 1
	v_mov_b64_e32 v[176:177], 0x3ff
	v_writelane_b32 v253, s5, 45
	s_cselect_b64 s[4:5], -1, 0
	v_writelane_b32 v253, s4, 46
	s_cmp_eq_u32 s24, 0
	v_mov_b64_e32 v[178:179], 0x107f
	v_writelane_b32 v253, s5, 47
	s_cselect_b64 s[4:5], -1, 0
	s_lshl_b32 s1, s24, 8
	v_writelane_b32 v253, s4, 48
	s_add_u32 s1, s64, s1
	v_mov_b32_e32 v226, 0x3e38aa3b
	v_writelane_b32 v253, s5, 49
	s_addc_u32 s4, s65, 0
	s_add_u32 s8, s1, 0x1400
	s_addc_u32 s9, s4, 0
	v_writelane_b32 v253, s8, 50
	v_mov_b32_e32 v227, 0x41b17218
	v_mov_b64_e32 v[180:181], 0x200
	v_writelane_b32 v253, s9, 51
	s_add_u32 s8, s1, 0x2400
	s_addc_u32 s9, s4, 0
	v_writelane_b32 v253, s8, 52
	s_add_u32 s4, s64, 0x3400
	s_addc_u32 s5, s65, 0
	v_writelane_b32 v253, s9, 53
	v_writelane_b32 v253, s4, 54
	v_mov_b64_e32 v[182:183], 0x1ff
	v_mov_b32_e32 v228, 0x437f0000
	v_writelane_b32 v253, s5, 55
	s_add_u32 s4, s64, 0x3500
	s_addc_u32 s5, s65, 0
	v_writelane_b32 v253, s4, 56
	s_cmpk_lt_i32 s67, 0x1600
	s_mov_b32 s62, 0xf800000
	v_writelane_b32 v253, s5, 57
	s_cselect_b64 s[4:5], -1, 0
	v_writelane_b32 v253, s4, 58
	s_ashr_i32 s1, s67, 31
	s_movk_i32 s97, 0x1800
	v_writelane_b32 v253, s5, 59
	v_writelane_b32 v253, s1, 60
	s_lshr_b32 s1, s1, 29
	s_add_i32 s1, s67, s1
	s_ashr_i32 s7, s1, 3
	s_and_b32 s1, s1, -8
	s_sub_i32 s1, s67, s1
	s_ashr_i32 s4, s3, 31
	s_cmpk_lt_i32 s67, 0x400
	v_writelane_b32 v253, s4, 61
	s_cselect_b64 s[4:5], -1, 0
	v_writelane_b32 v253, s4, 62
	s_movk_i32 s75, 0x800
	s_mov_b32 s33, 0x437e0000
	v_writelane_b32 v253, s5, 63
	s_lshl_b32 s4, s1, 7
	s_cmpk_lt_i32 s67, 0x1080
	s_cselect_b64 s[8:9], -1, 0
	v_writelane_b32 v254, s8, 0
	s_add_u32 s5, s42, 0x10000
	s_movk_i32 s48, 0x2ff
	v_writelane_b32 v254, s9, 1
	v_writelane_b32 v254, s5, 2
	s_addc_u32 s5, s43, 0
	v_writelane_b32 v254, s5, 3
;     __device__ bool next(int ii, Unit& u) const {
;         const int i = ii / NS; u.n = ii - i * NS;
;         const long L = (long)i * G + c; if (L >= nwg) return false;
;         int wgid = (int)L; { const int q = nwg / NXCD, r = nwg % NXCD, xcd = wgid % NXCD, off = wgid / NXCD; wgid = (xcd < r ? xcd * (q + 1) : r * (q + 1) + (xcd - r) * q) + off; }
;         const int nig = WGM * nN, gid = wgid / nig, fm = gid * WGM, gsz = (nM - fm) < WGM ? (nM - fm) : WGM;
;         u.pm = fm + ((wgid % nig) % gsz); u.pn = (wgid % nig) / gsz; return true;
; template <class Epi>
; __device__ __forceinline__ void gemm_phase(LAS unsigned char* lds, const Gemm g, const StaticOrder& S, const Epi& E, const int tid) {
;     ...
;     Unit cur, nxt; int ui = 0;
;     if (!S.next(0, cur)) return;
	s_add_u32 s5, s42, 0x31800400
	v_writelane_b32 v254, s5, 4
	s_addc_u32 s5, s43, 0
	v_writelane_b32 v254, s5, 5
	s_add_u32 s5, s42, 0x31800800
	v_writelane_b32 v254, s5, 6
	s_addc_u32 s5, s43, 0
	v_writelane_b32 v254, s5, 7
	s_add_u32 s5, s42, 0x29800800
	v_writelane_b32 v254, s5, 8
	s_addc_u32 s5, s43, 0
	v_writelane_b32 v254, s5, 9
	s_add_u32 s5, s42, 0x29801000
	v_writelane_b32 v254, s5, 10
	s_addc_u32 s5, s43, 0
	s_cmpk_lt_i32 s67, 0x200
	v_writelane_b32 v254, s5, 11
	s_cselect_b64 s[8:9], -1, 0
	v_writelane_b32 v254, s8, 12
	s_lshl_b32 s5, s1, 6
	s_cmp_lt_i32 s1, 0
	v_writelane_b32 v254, s9, 13
	s_mul_i32 s8, s1, 0x81
	s_cselect_b32 s8, s8, s4
	s_mul_i32 s4, s1, 0x41
	s_cselect_b32 s9, s4, s5
	s_movk_i32 s4, 0x2c1
	s_cselect_b32 s4, s4, 0x2c0
	s_mul_i32 s4, s1, s4
	s_movk_i32 s5, 0x211
	s_cselect_b32 s10, s5, 0x210
	s_add_i32 s4, s4, s7
	s_mul_hi_i32 s5, s4, 0x2e8ba2e9
	s_lshr_b32 s11, s5, 31
	s_ashr_i32 s5, s5, 6
	s_add_i32 s5, s5, s11
	s_mul_i32 s11, s5, 0x160
	s_sub_i32 s4, s4, s11
	s_bfe_u32 s11, s4, 0x3001c
	s_add_i32 s11, s4, s11
	s_and_b32 s12, s11, 0xfff8
	s_sub_i32 s4, s4, s12
	s_lshl_b32 s5, s5, 3
	s_sext_i32_i16 s11, s11
	s_sext_i32_i16 s4, s4
	s_add_i32 s12, s5, s4
	s_ashr_i32 s4, s11, 3
	v_writelane_b32 v254, s4, 14
	s_lshr_b32 s4, s11, 3
	s_bfe_i64 s[4:5], s[4:5], 0x100000
	s_lshl_b64 s[4:5], s[4:5], 20
	v_writelane_b32 v254, s4, 15
	s_ashr_i32 s13, s12, 31
	s_mul_i32 s1, s1, s10
	v_writelane_b32 v254, s5, 16
	s_mov_b32 s4, s12
	v_writelane_b32 v254, s4, 17
	s_movk_i32 s50, 0x1c00
	s_mov_b32 s51, 0x29801000
	v_writelane_b32 v254, s5, 18
	s_lshl_b64 s[4:5], s[12:13], 20
	s_add_u32 s4, s58, s4
	s_addc_u32 s5, s59, s5
	s_add_u32 s12, s4, 0x80000
	v_writelane_b32 v254, s4, 19
	s_addc_u32 s13, s5, 0
	s_mov_b32 s63, 0x31800000
	v_writelane_b32 v254, s5, 20
	s_add_i32 s4, s8, s7
	s_ashr_i32 s5, s4, 31
	s_lshr_b32 s5, s5, 27
	s_add_i32 s5, s4, s5
	s_and_b32 s8, s5, 0xffe0
	s_sub_i32 s4, s4, s8
	s_bfe_i32 s8, s4, 0x80000
	s_bfe_u32 s8, s8, 0x3000c
	s_add_i32 s8, s4, s8
	s_and_b32 s11, s8, 0xfc
	s_sub_i32 s4, s4, s11
	s_ashr_i32 s5, s5, 5
	s_bfe_i32 s8, s8, 0x80000
	s_lshl_b32 s5, s5, 2
	s_sext_i32_i16 s8, s8
	s_sext_i32_i8 s4, s4
	v_writelane_b32 v254, s12, 21
	s_add_i32 s14, s5, s4
	s_lshr_b32 s4, s8, 2
	v_writelane_b32 v254, s13, 22
	s_ashr_i32 s15, s14, 31
	s_ashr_i32 s13, s8, 2
	s_bfe_i64 s[4:5], s[4:5], 0x100000
	s_mul_i32 s11, s14, 0x2c0000
	s_mul_hi_i32 s8, s14, 0x2c0000
	s_add_u32 s16, s26, s11
	v_writelane_b32 v254, s26, 23
	s_addc_u32 s17, s27, s8
	s_add_u32 s10, s16, 0x160000
	v_writelane_b32 v254, s27, 24
	v_writelane_b32 v254, s16, 25
	s_addc_u32 s11, s17, 0
	s_add_i32 s1, s1, s7
	v_writelane_b32 v254, s17, 26
	v_writelane_b32 v254, s10, 27
	s_mul_hi_i32 s8, s1, 0x3e0f83e1
	s_add_i32 s7, s9, s7
	v_writelane_b32 v254, s11, 28
	s_lshr_b32 s10, s8, 31
	s_ashr_i32 s8, s8, 7
	s_add_i32 s8, s8, s10
	s_mul_i32 s10, s8, 0x210
	s_sub_i32 s1, s1, s10
	s_bfe_u32 s10, s1, 0x3001c
	s_ashr_i32 s9, s7, 31
	s_add_i32 s10, s1, s10
	s_lshr_b32 s9, s9, 26
	s_and_b32 s11, s10, 0xfff8
	s_add_i32 s9, s7, s9
	s_sub_i32 s1, s1, s11
	s_and_b32 s11, s9, 0xffc0
	s_sub_i32 s7, s7, s11
	s_bfe_i32 s11, s7, 0x80000
	s_bfe_u32 s11, s11, 0x3000c
	s_add_i32 s11, s7, s11
	s_and_b32 s12, s11, 0xf8
	s_sub_i32 s7, s7, s12
	s_ashr_i32 s9, s9, 6
	s_lshl_b32 s9, s9, 3
	s_sext_i32_i8 s7, s7
	s_add_i32 s12, s9, s7
	s_lshl_b32 s7, s8, 3
	s_sext_i32_i16 s1, s1
	s_add_i32 s16, s7, s1
	s_bfe_i32 s1, s11, 0x80000
	s_sext_i32_i16 s1, s1
	s_lshr_b32 s8, s1, 3
	s_ashr_i32 s7, s1, 3
	s_bfe_i64 s[8:9], s[8:9], 0x100000
	v_writelane_b32 v254, s7, 29
	s_lshl_b64 s[8:9], s[8:9], 19
	s_sext_i32_i16 s10, s10
	v_writelane_b32 v254, s8, 30
	s_ashr_i32 s1, s10, 3
	s_mul_i32 s7, s12, 0x180000
	v_writelane_b32 v254, s9, 31
	v_writelane_b32 v254, s1, 32
	s_lshr_b32 s8, s10, 3
	v_writelane_b32 v254, s12, 33
	s_mul_hi_i32 s1, s12, 0x180000
	v_writelane_b32 v254, s2, 34
	s_add_u32 s10, s2, s7
	v_writelane_b32 v254, s25, 35
	s_addc_u32 s11, s25, s1
	s_add_u32 s18, s10, 0xc0000
	v_writelane_b32 v254, s10, 36
	s_addc_u32 s19, s11, 0
	s_lshl_b64 s[4:5], s[4:5], 20
	v_writelane_b32 v254, s11, 37
	v_writelane_b32 v254, s18, 38
	s_mov_b32 s2, s14
	s_mul_hi_i32 s1, s0, 0x4800
	v_writelane_b32 v254, s19, 39
	v_writelane_b32 v254, s4, 40
	s_mulk_i32 s0, 0x4800
	s_mov_b32 s26, 0x1b800000
	v_writelane_b32 v254, s5, 41
	v_writelane_b32 v254, s2, 42
	s_lshl_b64 s[4:5], s[14:15], 20
	s_add_u32 s4, s58, s4
	v_writelane_b32 v254, s3, 43
	v_writelane_b32 v254, s0, 44
	s_addc_u32 s5, s59, s5
	s_mov_b32 s2, 1
	v_writelane_b32 v254, s1, 45
	s_add_u32 s0, s4, 0x80000
	v_writelane_b32 v254, s4, 46
	s_addc_u32 s1, s5, 0
	s_ashr_i32 s17, s16, 31
	v_writelane_b32 v254, s5, 47
	v_writelane_b32 v254, s0, 48
	s_add_i32 s54, 0, 0x22180
	s_movk_i32 s49, 0x300
	v_writelane_b32 v254, s1, 49
	s_bfe_i64 s[0:1], s[8:9], 0x100000
	s_lshl_b64 s[0:1], s[0:1], 20
	v_writelane_b32 v254, s0, 50
	s_mov_b32 s94, 0x800000
	s_mov_b32 s95, 0x3f317217
	v_writelane_b32 v254, s1, 51
	s_mul_hi_i32 s0, s13, 0x2c0000
	v_writelane_b32 v254, s0, 52
	v_writelane_b32 v254, s13, 53
	s_mul_i32 s0, s13, 0x2c0000
	v_writelane_b32 v254, s0, 54
	v_cmp_eq_u32_e64 s[0:1], 0, v0
	s_mov_b32 s66, 0x7f800000
	s_mov_b64 s[4:5], -1
	v_writelane_b32 v254, s0, 55
	s_mov_b64 s[28:29], 0x80
	s_mov_b32 s74, 0xbfb8aa3b
	v_writelane_b32 v254, s1, 56
	s_mov_b32 s0, s16
	v_writelane_b32 v254, s0, 57
	s_mov_b64 s[52:53], 0x60000
	s_mov_b32 s10, s61
	v_writelane_b32 v254, s1, 58
	s_lshl_b64 s[0:1], s[16:17], 20
	v_writelane_b32 v254, s0, 59
	v_readlane_b32 s20, v252, 31
	v_readlane_b32 s21, v252, 32
	v_writelane_b32 v254, s1, 60
	v_writelane_b32 v254, s67, 61
	v_writelane_b32 v254, s58, 62
	v_writelane_b32 v254, s59, 63
	v_readlane_b32 s22, v252, 33
	v_readlane_b32 s23, v252, 34

; #define PG8_STAGE(bufoff, gbase, voff) do { _Pragma("unroll") for (int _i = 0; _i < 2; ++_i) \
;         __builtin_amdgcn_global_load_lds((const unsigned*)((const char*)(gbase) + (voff)[_i]), (LAS unsigned*)(lds + (bufoff) + ldsw + _i * 8192), 16, 0, 0); } while (0)
; #define PG8_WAIT_V(n) asm volatile("s_waitcnt vmcnt(" #n ")" ::: "memory")
; #define PG8_BAR __builtin_amdgcn_s_barrier()
; template <class Epi>
; __device__ __forceinline__ void gemm_phase(LAS unsigned char* lds, const Gemm g, const StaticOrder& S, const Epi& E, const int tid) {
;     const int wid = __builtin_amdgcn_readfirstlane(tid >> 6), lane = tid & 63, wr = wid >> 2, wc = wid & 3, fr = lane & 15, fq = lane >> 4;
;     const int K = g.K, nt = K / BK;
;     unsigned voffA[2], voffB[2];
; #pragma unroll
;     for (int i = 0; i < 2; ++i) { int R, C; stage_rc(tid * 16 + i * 8192, R, C); const int Rb = Epi::PERM ? ((R & ~31) + perm32(R & 31)) : R;
;         voffA[i] = (unsigned)(R * g.lda + C) * 2u; voffB[i] = (unsigned)(Rb * g.ldb + C) * 2u; }
;     const size_t kstep = (size_t)(BK * 2);
;     const size_t hsA = (size_t)HALF * g.lda * 2, hsB = (size_t)HALF * g.ldb * 2;
;     const size_t tsA = 2 * hsA, tsB = 2 * hsB;
;     const unsigned ldsw = (unsigned)wid * 1024u;
;     const int aoff = lds_byte(wr * 64 + fr, fq * 8), boff = lds_byte(wc * 32 + fr, fq * 8);
;     ...
;     Unit cur, nxt; int ui = 0;
;     if (!S.next(0, cur)) return;
;     f32x4 acc[2][2][4][2];
; #pragma unroll
;     for (int a = 0; a < 2; ++a)
; #pragma unroll
;         for (int b = 0; b < 2; ++b)
; #pragma unroll
;             for (int m = 0; m < 4; ++m)
; #pragma unroll
;                 for (int n = 0; n < 2; ++n) acc[a][b][m][n] = (f32x4){0.f, 0.f, 0.f, 0.f};
;     bf16x8 At[4][2], B0[2][2], B1[2][2];
;     const char* cA = PG8_APTR(cur); const char* cB = PG8_BPTR(cur);
;     PG8_STAGE(PG8_SB(0, 0), cB, voffB); PG8_STAGE(PG8_SB(0, 1), cB + hsB, voffB); PG8_STAGE(PG8_SA(0, 0), cA, voffA); PG8_STAGE(PG8_SA(0, 1), cA + hsA, voffA);
;     if (wr == 1) PG8_BAR;
;     PG8_WAIT_V(2); PG8_BAR;
;     PG8_STAGE(PG8_SB(1, 0), cB + kstep, voffB); PG8_STAGE(PG8_SA(1, 0), cA + kstep, voffA); PG8_STAGE(PG8_SB(1, 1), cB + hsB + kstep, voffB);
;     PG8_WAIT_V(6); PG8_BAR;
.LBB0_151:
	s_cmp_le_i32 s44, s27
	s_cselect_b64 s[0:1], -1, 0
	s_cmp_lt_i32 s27, s45
	s_cselect_b64 s[6:7], -1, 0
	s_and_b64 s[6:7], s[0:1], s[6:7]
	v_readlane_b32 s0, v255, 0
	v_readlane_b32 s1, v255, 1
	s_mul_i32 s0, s0, 0x5800000
	v_writelane_b32 v255, s0, 4
	v_readlane_b32 s0, v253, 58
	v_readlane_b32 s1, v253, 59
	s_andn2_b64 vcc, exec, s[6:7]
	s_waitcnt vmcnt(0)
	v_cndmask_b32_e64 v0, 0, 1, s[0:1]
	v_cmp_ne_u32_e64 s[0:1], 1, v0
	s_nop 1
	v_writelane_b32 v255, s0, 5
	s_nop 1
	v_writelane_b32 v255, s1, 6
	v_writelane_b32 v255, s2, 7
	s_cbranch_vccnz .LBB0_168
	v_readlane_b32 s0, v255, 5
	v_readlane_b32 s1, v255, 6
	s_and_b64 vcc, exec, s[0:1]
	v_readfirstlane_b32 s10, v214
	s_cbranch_vccnz .LBB0_168
	v_bfe_i32 v1, v214, 27, 1
	v_lshlrev_b32_e32 v3, 4, v214
	v_lshrrev_b32_e32 v1, 22, v1
	v_ashrrev_i32_e32 v0, 31, v214
	v_add_u32_e32 v1, v3, v1
	v_lshrrev_b32_e32 v0, 26, v0
	v_and_b32_e32 v1, 0xfffffc00, v1
	v_add_u32_e32 v0, v214, v0
	v_sub_u32_e32 v1, v3, v1
	v_ashrrev_i32_e32 v0, 6, v0
	v_lshrrev_b32_e32 v2, 4, v1
	v_bitop3_b32 v2, v2, v1, 32 bitop3:0x6c
	v_lshlrev_b32_e32 v1, 3, v0
	v_and_b32_e32 v4, -16, v1
	v_ashrrev_i32_e32 v1, 31, v2
	v_lshrrev_b32_e32 v1, 26, v1
	v_add_u32_e32 v5, v2, v1
	v_ashrrev_i32_e32 v1, 6, v5
	v_and_b32_e32 v5, 0xc0, v5
	s_ashr_i32 s11, s10, 6
	v_sub_u32_e32 v2, v2, v5
	s_ashr_i32 s12, s10, 8
	s_lshl_b32 s27, s11, 10
	v_readlane_b32 s0, v252, 61
	v_readlane_b32 s1, v255, 4
	v_lshlrev_b32_e32 v6, 5, v0
	v_ashrrev_i16_sdwa v2, v225, sext(v2) dst_sel:DWORD dst_unused:UNUSED_PAD src0_sel:DWORD src1_sel:BYTE_0
	s_add_u32 s40, s0, s1
	v_readlane_b32 s0, v252, 62
	v_and_b32_e32 v6, 32, v6
	v_bfe_i32 v2, v2, 0, 16
	s_addc_u32 s41, s0, 0
	v_add_u32_e32 v4, v1, v4
	v_and_b32_e32 v8, 3, v1
	s_mov_b32 s0, 0xfffe0
	v_add_lshl_u32 v6, v6, v2, 1
	v_lshlrev_b32_e32 v5, 1, v4
	v_lshrrev_b32_e32 v7, 2, v4
	v_and_or_b32 v8, v4, s0, v8
	v_lshl_add_u32 v128, v4, 12, v6
	v_add_u32_e32 v4, 0x2000, v3
	v_ashrrev_i32_e32 v3, 31, v4
	v_lshrrev_b32_e32 v3, 22, v3
	v_and_b32_e32 v5, 24, v5
	v_and_b32_e32 v7, 4, v7
	v_add_u32_e32 v3, v4, v3
	v_or3_b32 v5, v8, v7, v5
	v_ashrrev_i32_e32 v3, 10, v3
	v_lshl_add_u32 v168, v5, 12, v6
	v_mul_i32_i24_e32 v5, 0x400, v3
	v_sub_u32_e32 v4, v4, v5
	v_lshrrev_b32_e32 v5, 4, v4
	v_bitop3_b32 v5, v5, v4, 32 bitop3:0x6c
	v_lshlrev_b32_e32 v4, 3, v3
	v_and_b32_e32 v6, -16, v4
	v_ashrrev_i32_e32 v4, 31, v5
	v_lshrrev_b32_e32 v4, 26, v4
	v_add_u32_e32 v7, v5, v4
	v_ashrrev_i32_e32 v4, 6, v7
	v_add_u32_e32 v6, v4, v6
	v_and_b32_e32 v10, 3, v4
	v_and_b32_e32 v7, 0xc0, v7
	v_and_or_b32 v10, v6, s0, v10
	v_readlane_b32 s0, v254, 15
	v_sub_u32_e32 v5, v5, v7
	v_readlane_b32 s1, v254, 16
	s_add_u32 s0, s40, s0
	v_lshlrev_b32_e32 v8, 5, v3
	v_ashrrev_i16_sdwa v5, v225, sext(v5) dst_sel:DWORD dst_unused:UNUSED_PAD src0_sel:DWORD src1_sel:BYTE_0
	v_lshlrev_b32_e32 v7, 1, v6
	v_lshrrev_b32_e32 v9, 2, v6
	s_addc_u32 s1, s41, s1
	s_add_i32 s42, s27, 0
	v_and_b32_e32 v8, 32, v8
	v_bfe_i32 v5, v5, 0, 16
	v_and_b32_e32 v7, 24, v7
	v_and_b32_e32 v9, 4, v9
	s_add_i32 m0, s42, 0x10000
	v_or3_b32 v7, v10, v9, v7
	v_add_lshl_u32 v8, v8, v5, 1
	global_load_lds_dwordx4 v168, s[0:1]
	s_add_i32 m0, s42, 0x12000
	v_lshl_add_u32 v132, v7, 12, v8
	s_add_u32 s8, s0, 0x80000
	global_load_lds_dwordx4 v132, s[0:1]
	s_addc_u32 s9, s1, 0
	s_add_i32 m0, s42, 0x14000
	s_add_i32 s43, s42, 0x2000
	global_load_lds_dwordx4 v168, s[8:9]
	s_add_i32 m0, s42, 0x16000
	v_lshl_add_u32 v130, v6, 12, v8
	global_load_lds_dwordx4 v132, s[8:9]
	v_readlane_b32 s8, v254, 19
	s_mov_b32 m0, s42
	v_readlane_b32 s9, v254, 20
	s_add_i32 s44, s42, 0x4000
	s_add_i32 s45, s42, 0x6000
	s_cmp_eq_u32 s12, 1
	s_nop 1
	global_load_lds_dwordx4 v128, s[8:9]
	s_mov_b32 m0, s43
	s_nop 0
	global_load_lds_dwordx4 v130, s[8:9]
	v_readlane_b32 s8, v254, 21
	s_mov_b32 m0, s44
	v_readlane_b32 s9, v254, 22
	s_nop 4
	global_load_lds_dwordx4 v128, s[8:9]
	s_mov_b32 m0, s45
	s_nop 0
	global_load_lds_dwordx4 v130, s[8:9]
	s_cselect_b64 s[8:9], -1, 0
	s_cmp_lg_u32 s12, 1
	s_cbranch_scc1 .LBB0_155
	s_barrier
.LBB0_155:
	v_mov_b32_e32 v133, v169
	v_lshl_add_u64 v[6:7], s[0:1], 0, v[168:169]
	v_readlane_b32 s34, v254, 19
	v_lshrrev_b32_e32 v14, 1, v214
	v_and_b32_e32 v15, 15, v214
	s_lshl_b32 s11, s11, 5
	v_mov_b32_e32 v129, v169
	v_lshl_add_u64 v[8:9], s[0:1], 0, v[132:133]
	v_readlane_b32 s35, v254, 20
	v_and_b32_e32 v14, 24, v14
	v_lshlrev_b32_e32 v16, 6, v15
	v_lshlrev_b32_e32 v17, 2, v214
	s_and_b32 s14, s11, 0x60
	s_add_i32 m0, s42, 0x18000
	v_lshl_add_u64 v[6:7], v[6:7], 0, s[28:29]
	v_mov_b32_e32 v131, v169
	v_lshl_add_u64 v[10:11], s[34:35], 0, v[128:129]
	v_lshl_or_b32 v16, v14, 1, v16
	v_and_b32_e32 v17, 32, v17
	v_lshl_or_b32 v142, s12, 6, v15
	s_lshl_b32 s12, s12, 13
	s_lshl_b32 s11, s14, 7
	s_waitcnt vmcnt(2)
	s_barrier
	global_load_lds_dwordx4 v[6:7], off
	v_lshl_add_u64 v[6:7], v[8:9], 0, s[28:29]
	s_add_i32 m0, s42, 0x1a000
	s_add_i32 s46, s42, 0x8000
	s_add_i32 s47, s42, 0xa000
	v_lshl_add_u64 v[12:13], s[34:35], 0, v[130:131]
	v_bitop3_b32 v15, v16, s12, v17 bitop3:0xde
	global_load_lds_dwordx4 v[6:7], off
	v_lshl_add_u64 v[6:7], v[10:11], 0, s[28:29]
	s_mov_b32 m0, s46
	s_add_u32 s12, s0, 0x80080
	global_load_lds_dwordx4 v[6:7], off
	v_lshl_add_u64 v[6:7], v[12:13], 0, s[28:29]
	s_mov_b32 m0, s47
	s_addc_u32 s13, s1, 0
	global_load_lds_dwordx4 v[6:7], off
	s_add_i32 m0, s42, 0x1c000
	v_lshl_add_u64 v[6:7], s[12:13], 0, v[168:169]
	global_load_lds_dwordx4 v[6:7], off
	v_lshl_add_u64 v[6:7], s[12:13], 0, v[132:133]
	s_add_i32 m0, s42, 0x1e000
	s_cmpk_lt_u32 s10, 0x100
	global_load_lds_dwordx4 v[6:7], off
	v_lshlrev_b32_e32 v6, 15, v0
	v_and_b32_e32 v6, 0xffff0000, v6
	v_lshl_add_u32 v1, v1, 12, v6
	v_and_b32_e32 v0, 1, v0
	v_lshl_or_b32 v0, v0, 6, v1
	v_lshl_add_u32 v134, v2, 1, v0
	v_lshlrev_b32_e32 v0, 15, v3
	v_and_b32_e32 v0, 0xffff0000, v0
	s_waitcnt vmcnt(6)
	v_lshl_add_u32 v0, v4, 12, v0
	v_and_b32_e32 v1, 1, v3
	v_lshl_or_b32 v0, v1, 6, v0
	v_readlane_b32 s12, v254, 17
	v_bitop3_b32 v143, s11, v16, v17 bitop3:0xf6
	s_cselect_b64 s[10:11], -1, 0
	v_or_b32_e32 v144, s14, v14
	v_mov_b32_e32 v135, v169
	v_lshl_add_u32 v136, v5, 1, v0
	v_mov_b32_e32 v137, v169
	s_mov_b32 s48, 0
	v_add_u32_e32 v145, 0, v15
	v_readlane_b32 s49, v254, 14
	s_mov_b32 s52, s12
	s_barrier
	v_readlane_b32 s13, v254, 18
	s_branch .LBB0_158

; #define PG8_STAGE(bufoff, gbase, voff) do { _Pragma("unroll") for (int _i = 0; _i < 2; ++_i) \
;         __builtin_amdgcn_global_load_lds((const unsigned*)((const char*)(gbase) + (voff)[_i]), (LAS unsigned*)(lds + (bufoff) + ldsw + _i * 8192), 16, 0, 0); } while (0)
; #define PG8_LDA(dst, b, h) do { _Pragma("unroll") for (int m = 0; m < 4; ++m) _Pragma("unroll") for (int k = 0; k < 2; ++k) dst[m][k] = *(const LAS bf16x8*)(lds + PG8_SA(b, h) + aoff + m * 2048 + k * 1024); } while (0)
; #define PG8_LDB(dst, b, h) do { _Pragma("unroll") for (int n = 0; n < 2; ++n) _Pragma("unroll") for (int k = 0; k < 2; ++k) dst[n][k] = *(const LAS bf16x8*)(lds + PG8_SB(b, h) + boff + n * 2048 + k * 1024); } while (0)
; #define PG8_MMA(ai, bj, At, Bt) do { __builtin_amdgcn_s_setprio(1); _Pragma("unroll") for (int m = 0; m < 4; ++m) _Pragma("unroll") for (int n = 0; n < 2; ++n) _Pragma("unroll") for (int k = 0; k < 2; ++k) \
;         acc[ai][bj][m][n] = __builtin_amdgcn_mfma_f32_16x16x32_bf16(Bt[n][k], At[m][k], acc[ai][bj][m][n], 0, 0, 0); __builtin_amdgcn_s_setprio(0); } while (0)
; #define PG8_WAIT_V(n) asm volatile("s_waitcnt vmcnt(" #n ")" ::: "memory")
; #define PG8_WAIT_L(n) asm volatile("s_waitcnt lgkmcnt(" #n ")" ::: "memory")
; #define PG8_BAR __builtin_amdgcn_s_barrier()
; #define PG8_SCHED __builtin_amdgcn_sched_barrier(0)
; template <class Epi>
; __device__ __forceinline__ void gemm_phase(LAS unsigned char* lds, const Gemm g, const StaticOrder& S, const Epi& E, const int tid) {
;     ...
;         for (int t = 0; t < nt; t += 2) {
;             const bool last = (t == nt - 2);
;             const char* a1 = cA + (size_t)(t + 1) * kstep;
;             const char* a2 = last ? nA : cA + (size_t)(t + 2) * kstep; const char* b2 = last ? nB : cB + (size_t)(t + 2) * kstep;
;             const char* a3 = a2 + kstep; const char* b3 = b2 + kstep;
;             PG8_LDB(B0, 0, 0); PG8_LDB(B1, 0, 1); PG8_SCHED; PG8_LDA(At, 0, 0); PG8_STAGE(PG8_SA(1, 1), a1 + hsA, voffA);
;             PG8_WAIT_V(8); PG8_WAIT_L(0); PG8_BAR; PG8_MMA(0, 0, At, B0); PG8_MMA(0, 1, At, B1); PG8_BAR; PG8_SCHED;
;             PG8_LDA(At, 0, 1); PG8_STAGE(PG8_SB(0, 0), b2, voffB); PG8_STAGE(PG8_SB(0, 1), b2 + hsB, voffB); PG8_STAGE(PG8_SA(0, 0), a2, voffA);
;             PG8_WAIT_V(8); PG8_WAIT_L(0); PG8_BAR; PG8_MMA(1, 0, At, B0); PG8_MMA(1, 1, At, B1); PG8_BAR; PG8_SCHED;
.LBB0_161:
	s_add_u32 s0, s34, 0xfff80080
	s_addc_u32 s1, s35, -1
	s_add_i32 s24, 0, 0x10000
	s_cmp_eq_u32 s59, 28
	s_cselect_b32 s39, s15, s1
	s_cselect_b32 s38, s53, s0
	s_cselect_b32 s1, s13, s58
	s_cselect_b32 s0, s56, s57
	s_add_i32 s25, 0, 0x14000
	v_add_u32_e32 v154, s24, v143
	v_add_u32_e32 v166, s25, v143
	ds_read_b128 v[138:141], v154
	ds_read_b128 v[146:149], v154 offset:1024
	ds_read_b128 v[150:153], v154 offset:2048
	ds_read_b128 v[154:157], v154 offset:3072
	ds_read_b128 v[158:161], v166
	ds_read_b128 v[162:165], v166 offset:1024
	ds_read_b128 v[184:187], v166 offset:2048
	ds_read_b128 v[188:191], v166 offset:3072
	v_lshl_add_u64 v[166:167], s[34:35], 0, v[134:135]
	s_add_i32 m0, s42, 0xc000
	ds_read_b128 v[192:195], v145
	ds_read_b128 v[196:199], v145 offset:1024
	ds_read_b128 v[200:203], v145 offset:2048
	ds_read_b128 v[204:207], v145 offset:3072
	ds_read_b128 v[208:211], v145 offset:4096
	ds_read_b128 v[230:233], v145 offset:5120
	ds_read_b128 v[234:237], v145 offset:6144
	ds_read_b128 v[238:241], v145 offset:7168
	global_load_lds_dwordx4 v[166:167], off
	v_lshl_add_u64 v[166:167], s[34:35], 0, v[136:137]
	s_add_i32 m0, s42, 0xe000
	s_nop 0
	global_load_lds_dwordx4 v[166:167], off
	s_waitcnt vmcnt(8)
	s_waitcnt lgkmcnt(0)
	s_barrier
	s_setprio 1
	s_waitcnt lgkmcnt(0)
	v_mfma_f32_16x16x32_bf16 v[124:127], v[138:141], v[192:195], v[124:127]
	v_mfma_f32_16x16x32_bf16 v[116:119], v[150:153], v[192:195], v[116:119]
	v_mfma_f32_16x16x32_bf16 v[108:111], v[138:141], v[200:203], v[108:111]
	v_mfma_f32_16x16x32_bf16 v[100:103], v[150:153], v[200:203], v[100:103]
	v_mfma_f32_16x16x32_bf16 v[92:95], v[138:141], v[208:211], v[92:95]
	v_mfma_f32_16x16x32_bf16 v[84:87], v[150:153], v[208:211], v[84:87]
	v_mfma_f32_16x16x32_bf16 v[76:79], v[138:141], v[234:237], v[76:79]
	v_mfma_f32_16x16x32_bf16 v[68:71], v[150:153], v[234:237], v[68:71]
	v_mfma_f32_16x16x32_bf16 v[124:127], v[146:149], v[196:199], v[124:127]
	v_mfma_f32_16x16x32_bf16 v[116:119], v[154:157], v[196:199], v[116:119]
	v_mfma_f32_16x16x32_bf16 v[108:111], v[146:149], v[204:207], v[108:111]
	v_mfma_f32_16x16x32_bf16 v[100:103], v[154:157], v[204:207], v[100:103]
	v_mfma_f32_16x16x32_bf16 v[92:95], v[146:149], v[230:233], v[92:95]
	v_mfma_f32_16x16x32_bf16 v[84:87], v[154:157], v[230:233], v[84:87]
	v_mfma_f32_16x16x32_bf16 v[76:79], v[146:149], v[238:241], v[76:79]
	v_mfma_f32_16x16x32_bf16 v[68:71], v[154:157], v[238:241], v[68:71]
	s_setprio 0
	s_setprio 1
	v_mfma_f32_16x16x32_bf16 v[120:123], v[158:161], v[192:195], v[120:123]
	v_mfma_f32_16x16x32_bf16 v[112:115], v[184:187], v[192:195], v[112:115]
	v_mfma_f32_16x16x32_bf16 v[104:107], v[158:161], v[200:203], v[104:107]
	v_mfma_f32_16x16x32_bf16 v[96:99], v[184:187], v[200:203], v[96:99]
	v_mfma_f32_16x16x32_bf16 v[88:91], v[158:161], v[208:211], v[88:91]
	v_mfma_f32_16x16x32_bf16 v[80:83], v[184:187], v[208:211], v[80:83]
	v_mfma_f32_16x16x32_bf16 v[72:75], v[158:161], v[234:237], v[72:75]
	v_mfma_f32_16x16x32_bf16 v[64:67], v[184:187], v[234:237], v[64:67]
	v_mfma_f32_16x16x32_bf16 v[120:123], v[162:165], v[196:199], v[120:123]
	v_mfma_f32_16x16x32_bf16 v[112:115], v[188:191], v[196:199], v[112:115]
	v_mfma_f32_16x16x32_bf16 v[104:107], v[162:165], v[204:207], v[104:107]
	v_mfma_f32_16x16x32_bf16 v[96:99], v[188:191], v[204:207], v[96:99]
	v_mfma_f32_16x16x32_bf16 v[88:91], v[162:165], v[230:233], v[88:91]
	v_mfma_f32_16x16x32_bf16 v[80:83], v[188:191], v[230:233], v[80:83]
	v_mfma_f32_16x16x32_bf16 v[72:75], v[162:165], v[238:241], v[72:75]
	v_mfma_f32_16x16x32_bf16 v[64:67], v[188:191], v[238:241], v[64:67]
	s_setprio 0
	s_barrier
	s_add_i32 s24, s24, s27
	v_lshl_add_u64 v[166:167], s[0:1], 0, v[168:169]
	s_mov_b32 m0, s24
	ds_read_b128 v[192:195], v145 offset:16384
	ds_read_b128 v[196:199], v145 offset:17408
	ds_read_b128 v[200:203], v145 offset:18432
	ds_read_b128 v[204:207], v145 offset:19456
	ds_read_b128 v[208:211], v145 offset:20480
	ds_read_b128 v[230:233], v145 offset:21504
	ds_read_b128 v[234:237], v145 offset:22528
	ds_read_b128 v[238:241], v145 offset:23552
	global_load_lds_dwordx4 v[166:167], off
	s_add_i32 m0, s24, 0x2000
	s_add_u32 s68, s0, 0x80000
	v_lshl_add_u64 v[212:213], s[0:1], 0, v[132:133]
	s_addc_u32 s69, s1, 0
	s_add_i32 s24, s25, s27
	global_load_lds_dwordx4 v[212:213], off
	v_lshl_add_u64 v[242:243], s[68:69], 0, v[168:169]
	s_mov_b32 m0, s24
	v_lshl_add_u64 v[244:245], s[38:39], 0, v[130:131]
	global_load_lds_dwordx4 v[242:243], off
	v_lshl_add_u64 v[242:243], s[68:69], 0, v[132:133]
	s_add_i32 m0, s24, 0x2000
	s_nop 0
	global_load_lds_dwordx4 v[242:243], off
	v_lshl_add_u64 v[242:243], s[38:39], 0, v[128:129]
	s_mov_b32 m0, s42
	s_nop 0
	global_load_lds_dwordx4 v[242:243], off
	s_mov_b32 m0, s43
	s_nop 0
	global_load_lds_dwordx4 v[244:245], off
	s_waitcnt vmcnt(8)
	s_waitcnt lgkmcnt(0)
	s_barrier
; #define PG8_STAGE(bufoff, gbase, voff) do { _Pragma("unroll") for (int _i = 0; _i < 2; ++_i) \
;         __builtin_amdgcn_global_load_lds((const unsigned*)((const char*)(gbase) + (voff)[_i]), (LAS unsigned*)(lds + (bufoff) + ldsw + _i * 8192), 16, 0, 0); } while (0)
; #define PG8_LDA(dst, b, h) do { _Pragma("unroll") for (int m = 0; m < 4; ++m) _Pragma("unroll") for (int k = 0; k < 2; ++k) dst[m][k] = *(const LAS bf16x8*)(lds + PG8_SA(b, h) + aoff + m * 2048 + k * 1024); } while (0)
; #define PG8_LDB(dst, b, h) do { _Pragma("unroll") for (int n = 0; n < 2; ++n) _Pragma("unroll") for (int k = 0; k < 2; ++k) dst[n][k] = *(const LAS bf16x8*)(lds + PG8_SB(b, h) + boff + n * 2048 + k * 1024); } while (0)
; #define PG8_MMA(ai, bj, At, Bt) do { __builtin_amdgcn_s_setprio(1); _Pragma("unroll") for (int m = 0; m < 4; ++m) _Pragma("unroll") for (int n = 0; n < 2; ++n) _Pragma("unroll") for (int k = 0; k < 2; ++k) \
;         acc[ai][bj][m][n] = __builtin_amdgcn_mfma_f32_16x16x32_bf16(Bt[n][k], At[m][k], acc[ai][bj][m][n], 0, 0, 0); __builtin_amdgcn_s_setprio(0); } while (0)
; #define PG8_WAIT_V(n) asm volatile("s_waitcnt vmcnt(" #n ")" ::: "memory")
; #define PG8_WAIT_L(n) asm volatile("s_waitcnt lgkmcnt(" #n ")" ::: "memory")
; #define PG8_BAR __builtin_amdgcn_s_barrier()
; #define PG8_SCHED __builtin_amdgcn_sched_barrier(0)
; template <class Epi>
; __device__ __forceinline__ void gemm_phase(LAS unsigned char* lds, const Gemm g, const StaticOrder& S, const Epi& E, const int tid) {
;     ...
;             PG8_WAIT_V(8); PG8_WAIT_L(0); PG8_BAR; PG8_MMA(1, 0, At, B0); PG8_MMA(1, 1, At, B1); PG8_BAR; PG8_SCHED;
;             PG8_LDB(B0, 1, 0); PG8_LDB(B1, 1, 1); PG8_SCHED; PG8_LDA(At, 1, 0); PG8_STAGE(PG8_SA(0, 1), a2 + hsA, voffA);
;             PG8_WAIT_V(8); PG8_WAIT_L(0); PG8_BAR; PG8_MMA(0, 0, At, B0); PG8_MMA(0, 1, At, B1); PG8_BAR; PG8_SCHED;
	s_setprio 1
	s_waitcnt lgkmcnt(0)
	v_mfma_f32_16x16x32_bf16 v[60:63], v[138:141], v[192:195], v[60:63]
	v_mfma_f32_16x16x32_bf16 v[52:55], v[150:153], v[192:195], v[52:55]
	v_mfma_f32_16x16x32_bf16 v[44:47], v[138:141], v[200:203], v[44:47]
	v_mfma_f32_16x16x32_bf16 v[36:39], v[150:153], v[200:203], v[36:39]
	v_mfma_f32_16x16x32_bf16 v[28:31], v[138:141], v[208:211], v[28:31]
	v_mfma_f32_16x16x32_bf16 v[20:23], v[150:153], v[208:211], v[20:23]
	v_mfma_f32_16x16x32_bf16 v[12:15], v[138:141], v[234:237], v[12:15]
	v_mfma_f32_16x16x32_bf16 v[4:7], v[150:153], v[234:237], v[4:7]
	v_mfma_f32_16x16x32_bf16 v[60:63], v[146:149], v[196:199], v[60:63]
	v_mfma_f32_16x16x32_bf16 v[52:55], v[154:157], v[196:199], v[52:55]
	v_mfma_f32_16x16x32_bf16 v[44:47], v[146:149], v[204:207], v[44:47]
	v_mfma_f32_16x16x32_bf16 v[36:39], v[154:157], v[204:207], v[36:39]
	v_mfma_f32_16x16x32_bf16 v[28:31], v[146:149], v[230:233], v[28:31]
	v_mfma_f32_16x16x32_bf16 v[20:23], v[154:157], v[230:233], v[20:23]
	v_mfma_f32_16x16x32_bf16 v[12:15], v[146:149], v[238:241], v[12:15]
	v_mfma_f32_16x16x32_bf16 v[4:7], v[154:157], v[238:241], v[4:7]
	s_setprio 0
	s_setprio 1
	v_mfma_f32_16x16x32_bf16 v[56:59], v[158:161], v[192:195], v[56:59]
	v_mfma_f32_16x16x32_bf16 v[48:51], v[184:187], v[192:195], v[48:51]
	v_mfma_f32_16x16x32_bf16 v[40:43], v[158:161], v[200:203], v[40:43]
	v_mfma_f32_16x16x32_bf16 v[32:35], v[184:187], v[200:203], v[32:35]
	v_mfma_f32_16x16x32_bf16 v[24:27], v[158:161], v[208:211], v[24:27]
	v_mfma_f32_16x16x32_bf16 v[16:19], v[184:187], v[208:211], v[16:19]
	v_mfma_f32_16x16x32_bf16 v[8:11], v[158:161], v[234:237], v[8:11]
	v_mfma_f32_16x16x32_bf16 v[0:3], v[184:187], v[234:237], v[0:3]
	v_mfma_f32_16x16x32_bf16 v[56:59], v[162:165], v[196:199], v[56:59]
	v_mfma_f32_16x16x32_bf16 v[48:51], v[188:191], v[196:199], v[48:51]
	v_mfma_f32_16x16x32_bf16 v[40:43], v[162:165], v[204:207], v[40:43]
	v_mfma_f32_16x16x32_bf16 v[32:35], v[188:191], v[204:207], v[32:35]
	v_mfma_f32_16x16x32_bf16 v[24:27], v[162:165], v[230:233], v[24:27]
	v_mfma_f32_16x16x32_bf16 v[16:19], v[188:191], v[230:233], v[16:19]
	v_mfma_f32_16x16x32_bf16 v[8:11], v[162:165], v[238:241], v[8:11]
	v_mfma_f32_16x16x32_bf16 v[0:3], v[188:191], v[238:241], v[0:3]
	s_setprio 0
	s_barrier
	s_add_i32 s24, 0, 0x18000
	s_add_i32 s25, 0, 0x1c000
	v_add_u32_e32 v154, s24, v143
	v_add_u32_e32 v170, s25, v143
	ds_read_b128 v[138:141], v154
	ds_read_b128 v[146:149], v154 offset:1024
	ds_read_b128 v[150:153], v154 offset:2048
	ds_read_b128 v[154:157], v154 offset:3072
	ds_read_b128 v[158:161], v170
	ds_read_b128 v[162:165], v170 offset:1024
	ds_read_b128 v[184:187], v170 offset:2048
	ds_read_b128 v[188:191], v170 offset:3072
	s_add_u32 s38, s38, 0x80000
	s_addc_u32 s39, s39, 0
	s_mov_b32 m0, s44
	v_lshl_add_u64 v[246:247], s[38:39], 0, v[128:129]
	ds_read_b128 v[192:195], v145 offset:32768
	ds_read_b128 v[196:199], v145 offset:33792
	ds_read_b128 v[200:203], v145 offset:34816
	ds_read_b128 v[204:207], v145 offset:35840
	ds_read_b128 v[208:211], v145 offset:36864
	ds_read_b128 v[230:233], v145 offset:37888
	ds_read_b128 v[234:237], v145 offset:38912
	ds_read_b128 v[238:241], v145 offset:39936
	global_load_lds_dwordx4 v[246:247], off
	v_lshl_add_u64 v[246:247], s[38:39], 0, v[130:131]
	s_mov_b32 m0, s45
	s_nop 0
	global_load_lds_dwordx4 v[246:247], off
	s_waitcnt vmcnt(8)
	s_waitcnt lgkmcnt(0)
	s_barrier
	s_setprio 1
	s_waitcnt lgkmcnt(0)
	v_mfma_f32_16x16x32_bf16 v[124:127], v[138:141], v[192:195], v[124:127]
	v_mfma_f32_16x16x32_bf16 v[116:119], v[150:153], v[192:195], v[116:119]
	v_mfma_f32_16x16x32_bf16 v[108:111], v[138:141], v[200:203], v[108:111]
	v_mfma_f32_16x16x32_bf16 v[100:103], v[150:153], v[200:203], v[100:103]
	v_mfma_f32_16x16x32_bf16 v[92:95], v[138:141], v[208:211], v[92:95]
	v_mfma_f32_16x16x32_bf16 v[84:87], v[150:153], v[208:211], v[84:87]
	v_mfma_f32_16x16x32_bf16 v[76:79], v[138:141], v[234:237], v[76:79]
	v_mfma_f32_16x16x32_bf16 v[68:71], v[150:153], v[234:237], v[68:71]
	v_mfma_f32_16x16x32_bf16 v[124:127], v[146:149], v[196:199], v[124:127]
	v_mfma_f32_16x16x32_bf16 v[116:119], v[154:157], v[196:199], v[116:119]
	v_mfma_f32_16x16x32_bf16 v[108:111], v[146:149], v[204:207], v[108:111]
	v_mfma_f32_16x16x32_bf16 v[100:103], v[154:157], v[204:207], v[100:103]
	v_mfma_f32_16x16x32_bf16 v[92:95], v[146:149], v[230:233], v[92:95]
	v_mfma_f32_16x16x32_bf16 v[84:87], v[154:157], v[230:233], v[84:87]
	v_mfma_f32_16x16x32_bf16 v[76:79], v[146:149], v[238:241], v[76:79]
	v_mfma_f32_16x16x32_bf16 v[68:71], v[154:157], v[238:241], v[68:71]
	s_setprio 0
	s_setprio 1
	v_mfma_f32_16x16x32_bf16 v[120:123], v[158:161], v[192:195], v[120:123]
	v_mfma_f32_16x16x32_bf16 v[112:115], v[184:187], v[192:195], v[112:115]
	v_mfma_f32_16x16x32_bf16 v[104:107], v[158:161], v[200:203], v[104:107]
	v_mfma_f32_16x16x32_bf16 v[96:99], v[184:187], v[200:203], v[96:99]
	v_mfma_f32_16x16x32_bf16 v[88:91], v[158:161], v[208:211], v[88:91]
	v_mfma_f32_16x16x32_bf16 v[80:83], v[184:187], v[208:211], v[80:83]
	v_mfma_f32_16x16x32_bf16 v[72:75], v[158:161], v[234:237], v[72:75]
	v_mfma_f32_16x16x32_bf16 v[64:67], v[184:187], v[234:237], v[64:67]
	v_mfma_f32_16x16x32_bf16 v[120:123], v[162:165], v[196:199], v[120:123]
	v_mfma_f32_16x16x32_bf16 v[112:115], v[188:191], v[196:199], v[112:115]
	v_mfma_f32_16x16x32_bf16 v[104:107], v[162:165], v[204:207], v[104:107]
	v_mfma_f32_16x16x32_bf16 v[96:99], v[188:191], v[204:207], v[96:99]
	v_mfma_f32_16x16x32_bf16 v[88:91], v[162:165], v[230:233], v[88:91]
	v_mfma_f32_16x16x32_bf16 v[80:83], v[188:191], v[230:233], v[80:83]
	v_mfma_f32_16x16x32_bf16 v[72:75], v[162:165], v[238:241], v[72:75]
	v_mfma_f32_16x16x32_bf16 v[64:67], v[188:191], v[238:241], v[64:67]
	s_setprio 0
	s_barrier
; #define PG8_STAGE(bufoff, gbase, voff) do { _Pragma("unroll") for (int _i = 0; _i < 2; ++_i) \
;         __builtin_amdgcn_global_load_lds((const unsigned*)((const char*)(gbase) + (voff)[_i]), (LAS unsigned*)(lds + (bufoff) + ldsw + _i * 8192), 16, 0, 0); } while (0)
; #define PG8_LDA(dst, b, h) do { _Pragma("unroll") for (int m = 0; m < 4; ++m) _Pragma("unroll") for (int k = 0; k < 2; ++k) dst[m][k] = *(const LAS bf16x8*)(lds + PG8_SA(b, h) + aoff + m * 2048 + k * 1024); } while (0)
; #define PG8_LDB(dst, b, h) do { _Pragma("unroll") for (int n = 0; n < 2; ++n) _Pragma("unroll") for (int k = 0; k < 2; ++k) dst[n][k] = *(const LAS bf16x8*)(lds + PG8_SB(b, h) + boff + n * 2048 + k * 1024); } while (0)
; #define PG8_MMA(ai, bj, At, Bt) do { __builtin_amdgcn_s_setprio(1); _Pragma("unroll") for (int m = 0; m < 4; ++m) _Pragma("unroll") for (int n = 0; n < 2; ++n) _Pragma("unroll") for (int k = 0; k < 2; ++k) \
;         acc[ai][bj][m][n] = __builtin_amdgcn_mfma_f32_16x16x32_bf16(Bt[n][k], At[m][k], acc[ai][bj][m][n], 0, 0, 0); __builtin_amdgcn_s_setprio(0); } while (0)
; #define PG8_WAIT_V(n) asm volatile("s_waitcnt vmcnt(" #n ")" ::: "memory")
; #define PG8_WAIT_L(n) asm volatile("s_waitcnt lgkmcnt(" #n ")" ::: "memory")
; #define PG8_BAR __builtin_amdgcn_s_barrier()
; #define PG8_SCHED __builtin_amdgcn_sched_barrier(0)
; template <class Epi>
; __device__ __forceinline__ void gemm_phase(LAS unsigned char* lds, const Gemm g, const StaticOrder& S, const Epi& E, const int tid) {
;     ...
;             PG8_WAIT_V(8); PG8_WAIT_L(0); PG8_BAR; PG8_MMA(1, 0, At, B0); PG8_MMA(1, 1, At, B1); PG8_BAR; PG8_SCHED;
;             PG8_LDB(B0, 1, 0); PG8_LDB(B1, 1, 1); PG8_SCHED; PG8_LDA(At, 1, 0); PG8_STAGE(PG8_SA(0, 1), a2 + hsA, voffA);
;             PG8_WAIT_V(8); PG8_WAIT_L(0); PG8_BAR; PG8_MMA(0, 0, At, B0); PG8_MMA(0, 1, At, B1); PG8_BAR; PG8_SCHED;
;             PG8_LDA(At, 1, 1); PG8_STAGE(PG8_SB(1, 0), b3, voffB); PG8_STAGE(PG8_SB(1, 1), b3 + hsB, voffB); PG8_STAGE(PG8_SA(1, 0), a3, voffA);
;             PG8_WAIT_V(8); PG8_WAIT_L(0); PG8_BAR; PG8_MMA(1, 0, At, B0); PG8_MMA(1, 1, At, B1); PG8_BAR; PG8_SCHED;
;         }
;         if (wr == 0) PG8_BAR;
	s_add_i32 s24, s24, s27
	v_lshl_add_u64 v[166:167], v[166:167], 0, s[28:29]
	s_mov_b32 m0, s24
	ds_read_b128 v[192:195], v145 offset:49152
	ds_read_b128 v[196:199], v145 offset:50176
	ds_read_b128 v[200:203], v145 offset:51200
	ds_read_b128 v[204:207], v145 offset:52224
	ds_read_b128 v[208:211], v145 offset:53248
	ds_read_b128 v[230:233], v145 offset:54272
	ds_read_b128 v[234:237], v145 offset:55296
	ds_read_b128 v[238:241], v145 offset:56320
	global_load_lds_dwordx4 v[166:167], off
	s_add_i32 m0, s24, 0x2000
	s_add_u32 s0, s0, 0x80080
	v_lshl_add_u64 v[166:167], v[212:213], 0, s[28:29]
	s_addc_u32 s1, s1, 0
	s_add_i32 s24, s25, s27
	global_load_lds_dwordx4 v[166:167], off
	v_lshl_add_u64 v[166:167], s[0:1], 0, v[168:169]
	s_mov_b32 m0, s24
	s_nop 0
	global_load_lds_dwordx4 v[166:167], off
	v_lshl_add_u64 v[166:167], s[0:1], 0, v[132:133]
	s_add_i32 m0, s24, 0x2000
	s_nop 0
	global_load_lds_dwordx4 v[166:167], off
	v_lshl_add_u64 v[166:167], v[242:243], 0, s[28:29]
	s_mov_b32 m0, s46
	s_nop 0
	global_load_lds_dwordx4 v[166:167], off
	v_lshl_add_u64 v[166:167], v[244:245], 0, s[28:29]
	s_mov_b32 m0, s47
	s_nop 0
	global_load_lds_dwordx4 v[166:167], off
	s_waitcnt vmcnt(8)
	s_waitcnt lgkmcnt(0)
	s_barrier
	s_setprio 1
	s_waitcnt lgkmcnt(0)
	v_mfma_f32_16x16x32_bf16 v[60:63], v[138:141], v[192:195], v[60:63]
	v_mfma_f32_16x16x32_bf16 v[52:55], v[150:153], v[192:195], v[52:55]
	v_mfma_f32_16x16x32_bf16 v[44:47], v[138:141], v[200:203], v[44:47]
	v_mfma_f32_16x16x32_bf16 v[36:39], v[150:153], v[200:203], v[36:39]
	v_mfma_f32_16x16x32_bf16 v[28:31], v[138:141], v[208:211], v[28:31]
	v_mfma_f32_16x16x32_bf16 v[20:23], v[150:153], v[208:211], v[20:23]
	v_mfma_f32_16x16x32_bf16 v[12:15], v[138:141], v[234:237], v[12:15]
	v_mfma_f32_16x16x32_bf16 v[4:7], v[150:153], v[234:237], v[4:7]
	v_mfma_f32_16x16x32_bf16 v[60:63], v[146:149], v[196:199], v[60:63]
	v_mfma_f32_16x16x32_bf16 v[52:55], v[154:157], v[196:199], v[52:55]
	v_mfma_f32_16x16x32_bf16 v[44:47], v[146:149], v[204:207], v[44:47]
	v_mfma_f32_16x16x32_bf16 v[36:39], v[154:157], v[204:207], v[36:39]
	v_mfma_f32_16x16x32_bf16 v[28:31], v[146:149], v[230:233], v[28:31]
	v_mfma_f32_16x16x32_bf16 v[20:23], v[154:157], v[230:233], v[20:23]
	v_mfma_f32_16x16x32_bf16 v[12:15], v[146:149], v[238:241], v[12:15]
	v_mfma_f32_16x16x32_bf16 v[4:7], v[154:157], v[238:241], v[4:7]
	s_setprio 0
	s_setprio 1
	v_mfma_f32_16x16x32_bf16 v[56:59], v[158:161], v[192:195], v[56:59]
	v_mfma_f32_16x16x32_bf16 v[48:51], v[184:187], v[192:195], v[48:51]
	v_mfma_f32_16x16x32_bf16 v[40:43], v[158:161], v[200:203], v[40:43]
	v_mfma_f32_16x16x32_bf16 v[32:35], v[184:187], v[200:203], v[32:35]
	v_mfma_f32_16x16x32_bf16 v[24:27], v[158:161], v[208:211], v[24:27]
	v_mfma_f32_16x16x32_bf16 v[16:19], v[184:187], v[208:211], v[16:19]
	v_mfma_f32_16x16x32_bf16 v[8:11], v[158:161], v[234:237], v[8:11]
	v_mfma_f32_16x16x32_bf16 v[0:3], v[184:187], v[234:237], v[0:3]
	v_mfma_f32_16x16x32_bf16 v[56:59], v[162:165], v[196:199], v[56:59]
	v_mfma_f32_16x16x32_bf16 v[48:51], v[188:191], v[196:199], v[48:51]
	v_mfma_f32_16x16x32_bf16 v[40:43], v[162:165], v[204:207], v[40:43]
	v_mfma_f32_16x16x32_bf16 v[32:35], v[188:191], v[204:207], v[32:35]
	v_mfma_f32_16x16x32_bf16 v[24:27], v[162:165], v[230:233], v[24:27]
	v_mfma_f32_16x16x32_bf16 v[16:19], v[188:191], v[230:233], v[16:19]
	v_mfma_f32_16x16x32_bf16 v[8:11], v[162:165], v[238:241], v[8:11]
	v_mfma_f32_16x16x32_bf16 v[0:3], v[188:191], v[238:241], v[0:3]
	s_setprio 0
	s_barrier
	s_add_i32 s59, s59, 2
	s_add_u32 s34, s34, 0x100
	s_addc_u32 s35, s35, 0
	s_add_u32 s57, s57, 0x100
	s_addc_u32 s58, s58, 0
	s_cmp_gt_u32 s59, 29
	s_cbranch_scc0 .LBB0_161
	s_and_b64 vcc, exec, s[10:11]
	s_cbranch_vccz .LBB0_164
	s_barrier

;     __device__ bool next(int ii, Unit& u) const {
;         const int i = ii / NS; u.n = ii - i * NS;
;         const long L = (long)i * G + c; if (L >= nwg) return false;
;         int wgid = (int)L; { const int q = nwg / NXCD, r = nwg % NXCD, xcd = wgid % NXCD, off = wgid / NXCD; wgid = (xcd < r ? xcd * (q + 1) : r * (q + 1) + (xcd - r) * q) + off; }
;         const int nig = WGM * nN, gid = wgid / nig, fm = gid * WGM, gsz = (nM - fm) < WGM ? (nM - fm) : WGM;
;         u.pm = fm + ((wgid % nig) % gsz); u.pn = (wgid % nig) / gsz; return true;
.LBB0_227:
	s_ashr_i32 s14, s16, 3
	s_add_i32 s14, s34, s14
	s_ashr_i32 s15, s14, 31
	s_lshr_b32 s15, s15, 27
	s_add_i32 s15, s14, s15
	s_ashr_i32 s16, s15, 5
	s_lshl_b32 s16, s16, 2
	s_sub_i32 s17, 0x80, s16
	s_min_i32 s17, s17, 4
	s_abs_i32 s24, s17
	v_cvt_f32_u32_e32 v0, s24
	s_sub_i32 s34, 0, s24
	s_andn2_b32 s15, s15, 31
	s_sub_i32 s14, s14, s15
	v_rcp_iflag_f32_e32 v0, v0
	s_abs_i32 s15, s14
	s_xor_b32 s25, s14, s17
	s_ashr_i32 s25, s25, 31
	v_mul_f32_e32 v0, 0x4f7ffffe, v0
	v_cvt_u32_f32_e32 v0, v0
	s_nop 0
	v_readfirstlane_b32 s35, v0
	s_mul_i32 s34, s34, s35
	s_mul_hi_u32 s34, s35, s34
	s_add_i32 s35, s35, s34
	s_mul_hi_u32 s34, s15, s35
	s_mul_i32 s35, s34, s24
	s_sub_i32 s15, s15, s35
	s_add_i32 s36, s34, 1
	s_sub_i32 s35, s15, s24
	s_cmp_ge_u32 s15, s24
	s_cselect_b32 s34, s36, s34
	s_cselect_b32 s15, s35, s15
	s_add_i32 s35, s34, 1
	s_cmp_ge_u32 s15, s24
	s_cselect_b32 s15, s35, s34
	s_xor_b32 s15, s15, s25
	s_sub_i32 s58, s15, s25
	s_mul_i32 s15, s58, s17
	s_sub_i32 s14, s14, s15
	s_add_i32 s59, s16, s14

;     __device__ bool next(int ii, Unit& u) const {
;         const int i = ii / NS; u.n = ii - i * NS;
;         const long L = (long)i * G + c; if (L >= nwg) return false;
;         int wgid = (int)L; { const int q = nwg / NXCD, r = nwg % NXCD, xcd = wgid % NXCD, off = wgid / NXCD; wgid = (xcd < r ? xcd * (q + 1) : r * (q + 1) + (xcd - r) * q) + off; }
;         const int nig = WGM * nN, gid = wgid / nig, fm = gid * WGM, gsz = (nM - fm) < WGM ? (nM - fm) : WGM;
;         u.pm = fm + ((wgid % nig) % gsz); u.pn = (wgid % nig) / gsz; return true;
.LBB0_891:
	s_ashr_i32 s2, s10, 3
	s_add_i32 s2, s12, s2
	s_ashr_i32 s8, s2, 31
	s_lshr_b32 s8, s8, 27
	s_add_i32 s8, s2, s8
	s_ashr_i32 s9, s8, 5
	s_lshl_b32 s9, s9, 2
	s_sub_i32 s10, 0x80, s9
	s_min_i32 s10, s10, 4
	s_abs_i32 s11, s10
	v_cvt_f32_u32_e32 v0, s11
	s_sub_i32 s13, 0, s11
	s_andn2_b32 s8, s8, 31
	s_sub_i32 s2, s2, s8
	v_rcp_iflag_f32_e32 v0, v0
	s_abs_i32 s8, s2
	s_xor_b32 s12, s2, s10
	s_ashr_i32 s12, s12, 31
	v_mul_f32_e32 v0, 0x4f7ffffe, v0
	v_cvt_u32_f32_e32 v0, v0
	s_nop 0
	v_readfirstlane_b32 s14, v0
	s_mul_i32 s13, s13, s14
	s_mul_hi_u32 s13, s14, s13
	s_add_i32 s14, s14, s13
	s_mul_hi_u32 s13, s8, s14
	s_mul_i32 s14, s13, s11
	s_sub_i32 s8, s8, s14
	s_add_i32 s15, s13, 1
	s_sub_i32 s14, s8, s11
	s_cmp_ge_u32 s8, s11
	s_cselect_b32 s13, s15, s13
	s_cselect_b32 s8, s14, s8
	s_add_i32 s14, s13, 1
	s_cmp_ge_u32 s8, s11
	s_cselect_b32 s8, s14, s13
	s_xor_b32 s8, s8, s12
	s_sub_i32 s8, s8, s12
	s_mul_i32 s10, s8, s10
	s_sub_i32 s2, s2, s10
	s_add_i32 s10, s9, s2

;     __device__ bool next(int ii, Unit& u) const {
;         const int i = ii / NS; u.n = ii - i * NS;
;         const long L = (long)i * G + c; if (L >= nwg) return false;
;         int wgid = (int)L; { const int q = nwg / NXCD, r = nwg % NXCD, xcd = wgid % NXCD, off = wgid / NXCD; wgid = (xcd < r ? xcd * (q + 1) : r * (q + 1) + (xcd - r) * q) + off; }
;         const int nig = WGM * nN, gid = wgid / nig, fm = gid * WGM, gsz = (nM - fm) < WGM ? (nM - fm) : WGM;
;         u.pm = fm + ((wgid % nig) % gsz); u.pn = (wgid % nig) / gsz; return true;
.LBB0_1070:
	s_ashr_i32 s2, s10, 3
	s_add_i32 s2, s14, s2
	s_ashr_i32 s8, s2, 31
	s_lshr_b32 s8, s8, 27
	s_add_i32 s8, s2, s8
	s_ashr_i32 s9, s8, 5
	s_lshl_b32 s9, s9, 2
	s_sub_i32 s10, 0x80, s9
	s_min_i32 s10, s10, 4
	s_abs_i32 s11, s10
	v_cvt_f32_u32_e32 v0, s11
	s_sub_i32 s15, 0, s11
	s_andn2_b32 s8, s8, 31
	s_sub_i32 s2, s2, s8
	v_rcp_iflag_f32_e32 v0, v0
	s_abs_i32 s8, s2
	s_xor_b32 s14, s2, s10
	s_ashr_i32 s14, s14, 31
	v_mul_f32_e32 v0, 0x4f7ffffe, v0
	v_cvt_u32_f32_e32 v0, v0
	s_nop 0
	v_readfirstlane_b32 s16, v0
	s_mul_i32 s15, s15, s16
	s_mul_hi_u32 s15, s16, s15
	s_add_i32 s16, s16, s15
	s_mul_hi_u32 s15, s8, s16
	s_mul_i32 s16, s15, s11
	s_sub_i32 s8, s8, s16
	s_add_i32 s17, s15, 1
	s_sub_i32 s16, s8, s11
	s_cmp_ge_u32 s8, s11
	s_cselect_b32 s15, s17, s15
	s_cselect_b32 s8, s16, s8
	s_add_i32 s16, s15, 1
	s_cmp_ge_u32 s8, s11
	s_cselect_b32 s8, s16, s15
	s_xor_b32 s8, s8, s14
	s_sub_i32 s47, s8, s14
	s_mul_i32 s8, s47, s10
	s_sub_i32 s2, s2, s8
	s_add_i32 s48, s9, s2
